# sparse-attention unit, compressed branch: LDS fragment reads double-buffered ahead of the dependent MFMA chain (MFMA shadow filled with next ds_read)
# speedup vs baseline: 1.0045x; 1.0045x over previous
.LBB0_683:
	s_or_b64 exec, exec, s[0:1]
	v_and_b32_e32 v70, 63, v1
	v_cmp_eq_u32_e64 s[0:1], 0, v1
	s_and_saveexec_b64 s[2:3], s[0:1]
	v_mov_b32_e32 v2, s87
	ds_write_b32 v2, v0
	s_or_b64 exec, exec, s[2:3]
	v_and_b32_e32 v107, 16, v15
	v_add_u32_e32 v10, 0, v107
	s_movk_i32 s2, 0x90
	v_mad_u32_u24 v11, v66, s2, v10
	s_waitcnt lgkmcnt(0)
	s_barrier
	ds_read_b128 v[2:5], v11 offset:35840
	ds_read_b128 v[6:9], v11 offset:35872
	s_waitcnt vmcnt(2) lgkmcnt(1)
	v_mfma_f32_32x32x16_bf16 v[50:65], v[2:5], v[88:91], 0
	ds_read_b128 v[2:5], v11 offset:35904
	v_mul_u32_u24_e32 v148, 0x90, v66
	s_cmp_gt_u32 s78, 7
	s_cselect_b64 s[2:3], -1, 0
	s_cmp_lt_u32 s78, 8
	v_add_u32_e32 v72, v10, v148
	v_mov_b32_e32 v18, 0
	s_waitcnt lgkmcnt(1)
	v_mfma_f32_32x32x16_bf16 v[50:65], v[6:9], v[80:83], v[50:65]
	v_mov_b32_e32 v19, 0
	v_mov_b32_e32 v20, 0
	v_mov_b32_e32 v21, 0
	v_mov_b32_e32 v22, 0
	v_mov_b32_e32 v23, 0
	v_mov_b32_e32 v24, 0
	v_mov_b32_e32 v25, 0
	s_waitcnt lgkmcnt(0)
	v_mfma_f32_32x32x16_bf16 v[50:65], v[2:5], v[84:87], v[50:65]
	ds_read_b128 v[2:5], v11 offset:35936
	v_mov_b32_e32 v26, 0
	v_mov_b32_e32 v27, 0
	v_mov_b32_e32 v28, 0
	v_mov_b32_e32 v29, 0
	v_mov_b32_e32 v30, 0
	v_mov_b32_e32 v31, 0
	s_waitcnt vmcnt(1) lgkmcnt(0)
	v_mfma_f32_32x32x16_bf16 v[50:65], v[2:5], v[92:95], v[50:65]
	ds_read_b128 v[2:5], v11 offset:54272
	v_mov_b32_e32 v32, 0
	v_mov_b32_e32 v33, 0
	s_waitcnt lgkmcnt(0)
	v_mfma_f32_32x32x16_bf16 v[50:65], v[2:5], v[88:91], v[50:65]
	ds_read_b128 v[2:5], v11 offset:54304
	ds_read_b128 v[214:217], v11 offset:54336
	s_waitcnt lgkmcnt(1)
	v_mfma_f32_32x32x16_bf16 v[50:65], v[2:5], v[80:83], v[50:65]
	ds_read_b128 v[2:5], v11 offset:54368
	s_waitcnt lgkmcnt(1)
	v_mfma_f32_32x32x16_bf16 v[50:65], v[214:217], v[84:87], v[50:65]
	s_waitcnt lgkmcnt(0)
	v_mfma_f32_32x32x16_bf16 v[50:65], v[2:5], v[92:95], v[50:65]
	v_mov_b32_e32 v2, 0
	s_cbranch_scc1 .LBB0_687
	ds_read_b128 v[4:7], v72 offset:40448
	ds_read_b128 v[214:217], v72 offset:40480
	s_waitcnt lgkmcnt(1)
	v_mfma_f32_32x32x16_bf16 v[18:33], v[4:7], v[88:91], 0
	ds_read_b128 v[4:7], v72 offset:40512
	s_waitcnt lgkmcnt(1)
	v_mfma_f32_32x32x16_bf16 v[18:33], v[214:217], v[80:83], v[18:33]
	ds_read_b128 v[214:217], v72 offset:40544
	s_waitcnt lgkmcnt(1)
	v_mfma_f32_32x32x16_bf16 v[18:33], v[4:7], v[84:87], v[18:33]
	ds_read_b128 v[4:7], v72 offset:58880
	s_waitcnt lgkmcnt(1)
	v_mfma_f32_32x32x16_bf16 v[18:33], v[214:217], v[92:95], v[18:33]
	ds_read_b128 v[214:217], v72 offset:58912
	s_waitcnt lgkmcnt(1)
	v_mfma_f32_32x32x16_bf16 v[18:33], v[4:7], v[88:91], v[18:33]
	ds_read_b128 v[4:7], v72 offset:58944
	s_waitcnt lgkmcnt(1)
	v_mfma_f32_32x32x16_bf16 v[18:33], v[214:217], v[80:83], v[18:33]
	ds_read_b128 v[214:217], v72 offset:58976
	s_waitcnt lgkmcnt(1)
	v_mfma_f32_32x32x16_bf16 v[18:33], v[4:7], v[84:87], v[18:33]
	s_waitcnt lgkmcnt(0)
	v_mfma_f32_32x32x16_bf16 v[18:33], v[214:217], v[92:95], v[18:33]
.LBB0_687:
	s_cmp_gt_u32 s78, 15
	s_cselect_b64 s[4:5], -1, 0
	s_cmp_lt_u32 s78, 16
	v_mov_b32_e32 v34, 0
	v_mov_b32_e32 v35, 0
	v_mov_b32_e32 v36, 0
	v_mov_b32_e32 v37, 0
	v_mov_b32_e32 v38, 0
	v_mov_b32_e32 v39, 0
	v_mov_b32_e32 v40, 0
	v_mov_b32_e32 v41, 0
	v_mov_b32_e32 v42, 0
	v_mov_b32_e32 v43, 0
	v_mov_b32_e32 v44, 0
	v_mov_b32_e32 v45, 0
	v_mov_b32_e32 v46, 0
	v_mov_b32_e32 v47, 0
	v_mov_b32_e32 v48, 0
	v_mov_b32_e32 v49, 0
	s_cbranch_scc1 .LBB0_689
	ds_read_b128 v[4:7], v72 offset:45056
	ds_read_b128 v[214:217], v72 offset:45088
	s_waitcnt lgkmcnt(1)
	v_mfma_f32_32x32x16_bf16 v[34:49], v[4:7], v[88:91], 0
	ds_read_b128 v[4:7], v72 offset:45120
	s_waitcnt lgkmcnt(1)
	v_mfma_f32_32x32x16_bf16 v[34:49], v[214:217], v[80:83], v[34:49]
	ds_read_b128 v[214:217], v72 offset:45152
	s_waitcnt lgkmcnt(1)
	v_mfma_f32_32x32x16_bf16 v[34:49], v[4:7], v[84:87], v[34:49]
	ds_read_b128 v[4:7], v72 offset:63488
	s_waitcnt lgkmcnt(1)
	v_mfma_f32_32x32x16_bf16 v[34:49], v[214:217], v[92:95], v[34:49]
	ds_read_b128 v[214:217], v72 offset:63520
	s_waitcnt lgkmcnt(1)
	v_mfma_f32_32x32x16_bf16 v[34:49], v[4:7], v[88:91], v[34:49]
	ds_read_b128 v[4:7], v72 offset:63552
	s_waitcnt lgkmcnt(1)
	v_mfma_f32_32x32x16_bf16 v[34:49], v[214:217], v[80:83], v[34:49]
	ds_read_b128 v[214:217], v72 offset:63584
	s_waitcnt lgkmcnt(1)
	v_mfma_f32_32x32x16_bf16 v[34:49], v[4:7], v[84:87], v[34:49]
	s_waitcnt lgkmcnt(0)
	v_mfma_f32_32x32x16_bf16 v[34:49], v[214:217], v[92:95], v[34:49]
.LBB0_689:
	s_cmp_gt_u32 s78, 23
	s_cselect_b64 s[6:7], -1, 0
	s_cmp_lt_u32 s78, 24
	v_mov_b32_e32 v3, 0
	v_mov_b32_e32 v4, 0
	v_mov_b32_e32 v5, 0
	v_mov_b32_e32 v6, 0
	v_mov_b32_e32 v7, 0
	v_mov_b32_e32 v8, 0
	v_mov_b32_e32 v9, 0
	v_mov_b32_e32 v10, 0
	v_mov_b32_e32 v11, 0
	v_mov_b32_e32 v12, 0
	v_mov_b32_e32 v13, 0
	v_mov_b32_e32 v14, 0
	v_mov_b32_e32 v15, 0
	v_mov_b32_e32 v16, 0
	v_mov_b32_e32 v17, 0
	s_cbranch_scc1 .LBB0_691
	ds_read_b128 v[2:5], v72 offset:49664
	ds_read_b128 v[74:77], v72 offset:49696
	v_add_u32_e32 v78, 0x3600, v72
	s_waitcnt lgkmcnt(1)
	v_mfma_f32_32x32x16_bf16 v[2:17], v[2:5], v[88:91], 0
	s_waitcnt lgkmcnt(0)
	v_mfma_f32_32x32x16_bf16 v[2:17], v[74:77], v[80:83], v[2:17]
	ds_read_b128 v[74:77], v72 offset:49728
	ds_read_b128 v[214:217], v72 offset:49760
	s_waitcnt lgkmcnt(1)
	v_mfma_f32_32x32x16_bf16 v[2:17], v[74:77], v[84:87], v[2:17]
	s_waitcnt lgkmcnt(0)
	v_mfma_f32_32x32x16_bf16 v[2:17], v[214:217], v[92:95], v[2:17]
	ds_read_b128 v[72:75], v78 offset:54272
	ds_read_b128 v[214:217], v78 offset:54304
	s_waitcnt lgkmcnt(1)
	v_mfma_f32_32x32x16_bf16 v[2:17], v[72:75], v[88:91], v[2:17]
	ds_read_b128 v[72:75], v78 offset:54336
	s_waitcnt lgkmcnt(1)
	v_mfma_f32_32x32x16_bf16 v[2:17], v[214:217], v[80:83], v[2:17]
	ds_read_b128 v[214:217], v78 offset:54368
	s_waitcnt lgkmcnt(1)
	v_mfma_f32_32x32x16_bf16 v[2:17], v[72:75], v[84:87], v[2:17]
	s_waitcnt lgkmcnt(0)
	v_mfma_f32_32x32x16_bf16 v[2:17], v[214:217], v[92:95], v[2:17]
